# mamba prefetch wait deferred to commit; mLSTM K^T gather via ds_read_b64_tr_b16 (32 u16 reads -> 8 transposed reads)
# speedup vs baseline: 1.0089x; 1.0089x over previous
.LBB0_653:
	ds_read_b32 v0, v74 offset:34944
	ds_read_b64 v[2:3], v75 offset:32768
	s_add_i32 s24, s22, 1
	s_cmpk_lg_i32 s22, 0x207
	s_cselect_b64 s[18:19], -1, 0
	s_cmpk_eq_i32 s22, 0x207
	s_waitcnt lgkmcnt(0)
	v_pk_mul_f32 v[0:1], v[0:1], v[2:3] op_sel_hi:[0,1]
	ds_write_b64 v75, v[0:1] offset:32768
	s_waitcnt lgkmcnt(0)
	s_barrier
	s_cbranch_scc1 .LBB0_667
	v_sub_co_u32_e64 v0, s[20:21], s22, 7
	s_and_b64 s[26:27], s[20:21], exec
	v_readfirstlane_b32 s23, v0
	s_cselect_b32 s23, s24, s23
	s_cselect_b32 s25, 7, 0x1ff
	s_sub_i32 s25, s25, s23
	s_and_b64 s[26:27], s[40:41], exec
	s_cselect_b32 s23, s23, s25
	s_and_b64 s[20:21], s[20:21], exec
	s_cselect_b32 s20, 0x4000, 0
	s_lshl_b32 s23, s23, 5
	s_add_i32 s23, s23, s20
	v_mov_b32_e32 v8, 0
	v_mov_b32_e32 v0, 0
	v_mov_b32_e32 v1, 0
	v_mov_b32_e32 v2, 0
	v_mov_b32_e32 v3, 0
	s_and_saveexec_b64 s[20:21], s[4:5]
	s_cbranch_execz .LBB0_656
	v_add_u32_e32 v0, s23, v80
	v_mad_i64_i32 v[0:1], s[26:27], v0, s95, v[52:53]
	global_load_dwordx4 v[18:21], v[0:1], off
.LBB0_656:
	s_or_b64 exec, exec, s[20:21]
	v_mov_b32_e32 v4, 0
	v_mov_b32_e32 v5, 0
	v_mov_b32_e32 v6, 0
	v_mov_b32_e32 v7, 0
	s_and_saveexec_b64 s[20:21], s[6:7]
	s_cbranch_execz .LBB0_658
	v_add_u32_e32 v4, s23, v81
	v_mad_i64_i32 v[4:5], s[26:27], v4, s95, v[54:55]
	global_load_dwordx4 v[22:25], v[4:5], off
.LBB0_658:
	s_or_b64 exec, exec, s[20:21]
	v_mov_b32_e32 v9, 0
	v_mov_b32_e32 v10, 0
	v_mov_b32_e32 v11, 0
	s_and_saveexec_b64 s[20:21], s[8:9]
	s_cbranch_execz .LBB0_660
	v_add_u32_e32 v8, s23, v83
	v_mad_i64_i32 v[8:9], s[26:27], v8, s95, v[56:57]
	global_load_dwordx4 v[26:29], v[8:9], off
.LBB0_660:
	s_or_b64 exec, exec, s[20:21]
	v_mov_b32_e32 v12, 0
	v_mov_b32_e32 v13, 0
	v_mov_b32_e32 v14, 0
	v_mov_b32_e32 v15, 0
	s_and_saveexec_b64 s[20:21], s[10:11]
	s_cbranch_execz .LBB0_662
	v_add_u32_e32 v12, s23, v84
	v_mad_i64_i32 v[12:13], s[26:27], v12, s95, v[58:59]
	global_load_dwordx4 v[30:33], v[12:13], off
.LBB0_662:
	s_or_b64 exec, exec, s[20:21]
	s_and_saveexec_b64 s[20:21], s[12:13]
	s_cbranch_execz .LBB0_664
	v_add_u32_e32 v0, s23, v85
	v_mad_i64_i32 v[0:1], s[26:27], v0, s95, v[60:61]
	global_load_dwordx4 v[34:37], v[0:1], off

.LBB0_674:
	s_or_b64 exec, exec, s[20:21]
	s_andn2_b64 vcc, exec, s[18:19]
	s_cbranch_vccnz .LBB0_652
	s_waitcnt vmcnt(0)
	s_and_saveexec_b64 s[18:19], s[4:5]
	s_cbranch_execz .LBB0_681
	v_lshlrev_b32_e32 v8, 16, v18
	v_and_b32_e32 v9, 0xffff0000, v18
	v_lshlrev_b32_e32 v10, 16, v19
	v_and_b32_e32 v11, 0xffff0000, v19
	v_lshlrev_b32_e32 v12, 16, v20
	v_and_b32_e32 v13, 0xffff0000, v20
	v_lshlrev_b32_e32 v14, 16, v21
	v_and_b32_e32 v15, 0xffff0000, v21
	ds_write_b128 v87, v[8:11]
	ds_write_b128 v87, v[12:15] offset:16
	s_or_b64 exec, exec, s[18:19]
	s_and_saveexec_b64 s[18:19], s[6:7]
	s_cbranch_execnz .LBB0_682

.LBB0_803:
	s_or_b64 exec, exec, s[18:19]
	s_mul_hi_i32 s18, s21, 0x2080000
	s_mul_i32 s21, s21, 0x2080000
	s_add_u32 s19, s12, s21
	s_addc_u32 s18, s13, s18
	s_lshl_b32 s21, s22, 1
	v_and_b32_e32 v84, 15, v110
	s_add_u32 s14, s14, s21
	v_lshlrev_b32_e32 v85, 1, v110
	s_addc_u32 s15, s15, 0
	s_lshl_b32 s20, s20, 4
	v_lshl_or_b32 v93, v111, 4, v84
	v_lshrrev_b32_e32 v86, 4, v82
	v_and_b32_e32 v88, 0xffffff80, v85
	s_add_u32 s62, s14, s20
	v_lshlrev_b32_e32 v85, 2, v82
	v_and_b32_e32 v82, 48, v82
	v_mul_lo_u32 v94, v93, s51
	s_addc_u32 s63, s15, 0
	v_readlane_b32 s24, v255, 4
	s_add_i32 s23, 0, 0x10a00
	v_add3_u32 v137, 0, v94, v82
	v_lshlrev_b32_e32 v94, 2, v93
	v_lshlrev_b32_e32 v141, 9, v86
	v_lshlrev_b32_e32 v89, 1, v84
	v_add_u32_e32 v132, s24, v85
	v_add_u32_e32 v133, s88, v85
	v_add_u32_e32 v134, s23, v85
	v_mul_u32_u24_e32 v92, 0x210, v84
	v_mad_u32_u24 v85, v84, s51, 0
	v_lshlrev_b32_e32 v135, 3, v86
	v_add_u32_e32 v139, s23, v94
	v_add_u32_e32 v95, 0, v141
	s_movk_i32 s23, 0xfe10
	v_mul_i32_i24_e32 v84, 0xfffffe40, v84
	v_add_u32_e32 v136, v85, v82
	v_add_u32_e32 v142, v95, v94
	v_mad_i32_i24 v95, v86, s23, v95
	v_add3_u32 v143, v85, v84, v135
	s_add_i32 s23, 0, 0x10200
	v_and_b32_e32 v85, 7, v110
	s_add_i32 s22, 0, 0x10b80
	v_add_u32_e32 v144, s23, v94
	v_ashrrev_i32_e32 v84, 3, v110
	v_lshlrev_b32_e32 v94, 5, v85
	v_add_lshl_u32 v94, v94, v84, 2
	s_add_u32 s19, s19, s21
	v_add_u32_e32 v145, s23, v94
	v_add_u32_e32 v146, 0, v94
	v_lshlrev_b32_e32 v94, 2, v84
	s_addc_u32 s21, s18, 0
	v_lshlrev_b32_e32 v87, 2, v86
	v_add_u32_e32 v96, s23, v94
	v_add_u32_e32 v148, 0, v94
	v_add_u32_e32 v149, s24, v94
	v_sub_u32_e32 v94, 31, v84
	s_add_u32 s18, s19, s20
	v_cndmask_b32_e64 v150, v94, v84, s[4:5]
	s_addc_u32 s19, s21, 0
	v_lshlrev_b32_e32 v84, 1, v85
	v_mov_b32_e32 v85, v17
	v_add_u32_e32 v154, s88, v82
	v_or_b32_e32 v82, 16, v87
	v_lshl_add_u64 v[84:85], s[18:19], 0, v[84:85]
	s_mov_b64 s[18:19], 0x6aa8000
	v_cmp_le_i32_e64 s[36:37], v82, v93
	v_lshl_add_u32 v158, v82, 2, s88
	v_or_b32_e32 v82, 17, v87
	v_lshl_add_u64 v[106:107], v[84:85], 0, s[18:19]
	s_movk_i32 s18, 0x1070
	v_cmp_le_i32_e64 s[38:39], v82, v93
	v_lshl_add_u32 v159, v82, 2, s88
	v_or_b32_e32 v82, 18, v87
	s_waitcnt lgkmcnt(0)
	v_mad_u32_u24 v84, v86, s18, v95
	v_lshl_add_u32 v153, v83, 4, s22
	v_or_b32_e32 v83, 1, v87
	v_cmp_le_i32_e64 s[40:41], v82, v93
	v_lshl_add_u32 v160, v82, 2, s88
	v_or_b32_e32 v82, 19, v87
	v_add3_u32 v90, 0, v88, v89
	v_and_b32_e32 v91, 31, v110
	v_lshl_add_u32 v151, v86, 5, s88
	v_add3_u32 v152, v84, v88, v89
	v_bfe_u32 v178, v119, 4, 2
	v_bfe_u32 v179, v119, 2, 2
	v_lshl_add_u32 v178, v178, 3, v179
	v_mul_u32_u24_e32 v178, 0x210, v178
	v_and_b32_e32 v179, 3, v119
	v_lshl_add_u32 v178, v179, 3, v178
	v_lshrrev_b32_e32 v179, 6, v119
	v_lshl_add_u32 v178, v179, 7, v178
	v_lshl_add_u64 v[108:109], s[16:17], 0, v[16:17]
	v_mul_u32_u24_e32 v16, 0x840, v86
	v_mul_u32_u24_e32 v84, 0x210, v83
	v_or_b32_e32 v85, 2, v87
	v_or_b32_e32 v86, 3, v87
	v_cmp_le_i32_e64 s[42:43], v82, v93
	v_lshl_add_u32 v161, v82, 2, s88
	v_mov_b32_e32 v82, 0
	v_cmp_gt_u32_e64 s[12:13], 64, v110
	v_lshl_add_u32 v131, v91, 4, s22
	v_cmp_lt_i32_e64 s[14:15], 1, v111
	v_add_u32_e32 v138, 0xffffbe00, v137
	v_add_u32_e32 v140, 0xffffff80, v139
	v_add_u32_e32 v147, 0x400, v96
	s_mov_b32 s52, 0
	v_cmp_eq_u32_e64 s[16:17], 0, v91
	v_cmp_gt_u32_e64 s[18:19], 2, v91
	v_cmp_gt_u32_e64 s[20:21], 4, v91
	v_cmp_gt_u32_e64 s[22:23], 8, v91
	v_cmp_gt_u32_e64 s[24:25], 16, v91
	v_cmp_le_i32_e64 s[26:27], v87, v93
	v_cmp_lt_i32_e64 s[28:29], v87, v93
	v_lshl_add_u32 v155, v83, 2, s88
	v_cmp_le_i32_e64 s[30:31], v85, v93
	v_lshl_add_u32 v156, v85, 2, s88
	v_cmp_le_i32_e64 s[34:35], v86, v93
	v_lshl_add_u32 v157, v86, 2, s88
	v_lshlrev_b32_e32 v162, 7, v83
	v_lshlrev_b32_e32 v163, 7, v85
	v_lshlrev_b32_e32 v164, 7, v86
	v_add_u32_e32 v165, v90, v16
	v_add_u32_e32 v166, v90, v84
	v_add_u32_e32 v167, v95, v92
	s_mov_b32 s77, 0
	v_mov_b32_e32 v83, v82
	v_mov_b32_e32 v84, v82
	v_mov_b32_e32 v85, v82
	v_mov_b32_e32 v86, v82
	v_mov_b32_e32 v87, v82
	v_mov_b32_e32 v88, v82
	v_mov_b32_e32 v89, v82
	v_mov_b32_e32 v90, v82
	v_mov_b32_e32 v91, v82
	v_mov_b32_e32 v92, v82
	v_mov_b32_e32 v93, v82
	v_mov_b32_e32 v94, v82
	v_mov_b32_e32 v95, v82
	v_mov_b32_e32 v96, v82
	v_mov_b32_e32 v97, v82
	s_barrier
	v_cndmask_b32_e64 v155, 0, v228, s[8:9]
	v_cndmask_b32_e64 v156, 0, v228, s[8:9]
	v_cndmask_b32_e64 v157, 0, v228, s[8:9]
	v_cndmask_b32_e64 v158, 0, v228, s[8:9]
	v_cndmask_b32_e64 v159, 0, v228, s[8:9]
	v_cndmask_b32_e64 v160, 0, v228, s[8:9]
	v_cndmask_b32_e64 v161, 0, v228, s[8:9]
	v_cndmask_b32_e64 v177, 0, v228, s[8:9]
	v_add_u32_e32 v155, v155, v122
	v_add_u32_e32 v156, v156, v123
	v_add_u32_e32 v157, v157, v124
	v_add_u32_e32 v158, v158, v125
	v_add_u32_e32 v159, v159, v126
	v_add_u32_e32 v160, v160, v127
	v_add_u32_e32 v161, v161, v128
	v_add_u32_e32 v177, v177, v129
	s_branch .LBB0_806

.LBB0_829:
	s_or_b64 exec, exec, s[44:45]
	v_sub_co_u32_e64 v16, s[44:45], s77, 8
	s_waitcnt lgkmcnt(14)
	v_mov_b32_e32 v98, s77
	s_and_b64 s[74:75], s[44:45], exec
	v_cndmask_b32_e64 v16, v16, v98, s[44:45]
	s_cselect_b32 s78, 7, 0x1ff
	v_sub_u32_e32 v98, s78, v16
	v_cndmask_b32_e64 v16, v98, v16, s[4:5]
	s_waitcnt lgkmcnt(0)
	s_barrier
	ds_read_b32 v216, v145
	ds_read_b32 v217, v146 offset:64000
	ds_read_b32 v218, v147
	ds_read_b32 v219, v148 offset:65024
	ds_read_b32 v220, v149
	s_cselect_b32 s74, 0x4000, 0
	v_add_u32_e32 v169, s74, v150
	v_add_u32_e32 v170, v143, v135
	v_lshl_add_u32 v222, v16, 5, v169
	v_mov_b32_e32 v221, s89
	ds_read_b32 v171, v221
	ds_read_b128 v[98:101], v170 offset:54272
	ds_read_b128 v[102:105], v151
	ds_read_b128 v[172:175], v151 offset:16
	s_waitcnt lgkmcnt(4)
	v_add_f32_e32 v216, v216, v217
	v_add_f32_e32 v218, v218, v219
	v_max_f32_e32 v220, v220, v220
	v_max_f32_e64 v218, |v218|, v220
	v_rcp_f32_e32 v218, v218
	v_ashrrev_i32_e32 v223, 31, v222
	v_lshlrev_b64 v[222:223], 11, v[222:223]
	v_mul_f32_e32 v216, v216, v218
	v_lshl_add_u64 v[222:223], v[106:107], 0, v[222:223]
	v_cvt_pk_bf16_f32 v220, v216, v17
	global_store_short v[222:223], v220, off
	ds_read_b64_tr_b16 v[180:181], v178 offset:16896
	ds_read_b64_tr_b16 v[182:183], v178 offset:19008
	ds_read_b64_tr_b16 v[184:185], v178 offset:16928
	ds_read_b64_tr_b16 v[186:187], v178 offset:19040
	ds_read_b64_tr_b16 v[188:189], v178 offset:16960
	ds_read_b64_tr_b16 v[190:191], v178 offset:19072
	ds_read_b64_tr_b16 v[192:193], v178 offset:16992
	ds_read_b64_tr_b16 v[194:195], v178 offset:19104
	s_waitcnt lgkmcnt(8)
	v_lshlrev_b32_e32 v176, 16, v98
	v_add_f32_e32 v103, v171, v103
	v_mul_f32_e32 v103, 0x3fb8aa3b, v103
	v_exp_f32_e32 v103, v103
	v_add_f32_e32 v102, v171, v102
	v_mul_f32_e32 v102, 0x3fb8aa3b, v102
	v_and_b32_e32 v98, 0xffff0000, v98
	v_exp_f32_e32 v102, v102
	v_mul_f32_e32 v98, v103, v98
	v_add_f32_e32 v103, v171, v104
	v_mul_f32_e32 v103, 0x3fb8aa3b, v103
	v_exp_f32_e32 v103, v103
	v_mul_f32_e32 v102, v102, v176
	v_cvt_pk_bf16_f32 v98, v102, v98
	v_lshlrev_b32_e32 v102, 16, v99
	v_mul_f32_e32 v102, v103, v102
	v_add_f32_e32 v103, v171, v105
	v_mul_f32_e32 v103, 0x3fb8aa3b, v103
	v_exp_f32_e32 v103, v103
	v_and_b32_e32 v99, 0xffff0000, v99
	v_mul_f32_e32 v16, 0x3fb8aa3b, v171
	v_exp_f32_e32 v16, v16
	v_mul_f32_e32 v99, v103, v99
	v_add_f32_e32 v103, v171, v172
	v_mul_f32_e32 v103, 0x3fb8aa3b, v103
	v_exp_f32_e32 v103, v103
	v_cvt_pk_bf16_f32 v99, v102, v99
	v_lshlrev_b32_e32 v102, 16, v100
	v_and_b32_e32 v100, 0xffff0000, v100
	v_mul_f32_e32 v102, v103, v102
	v_add_f32_e32 v103, v171, v173
	v_mul_f32_e32 v103, 0x3fb8aa3b, v103
	v_exp_f32_e32 v103, v103
	v_pk_mul_f32 v[96:97], v[96:97], v[16:17] op_sel_hi:[1,0]
	v_pk_mul_f32 v[94:95], v[94:95], v[16:17] op_sel_hi:[1,0]
	v_pk_mul_f32 v[92:93], v[92:93], v[16:17] op_sel_hi:[1,0]
	v_mul_f32_e32 v100, v103, v100
	v_add_f32_e32 v103, v171, v174
	v_mul_f32_e32 v103, 0x3fb8aa3b, v103
	v_exp_f32_e32 v103, v103
	v_cvt_pk_bf16_f32 v100, v102, v100
	v_lshlrev_b32_e32 v102, 16, v101
	v_and_b32_e32 v101, 0xffff0000, v101
	v_mul_f32_e32 v102, v103, v102
	v_add_f32_e32 v103, v171, v175
	v_mul_f32_e32 v103, 0x3fb8aa3b, v103
	v_exp_f32_e32 v103, v103
	v_pk_mul_f32 v[90:91], v[90:91], v[16:17] op_sel_hi:[1,0]
	v_pk_mul_f32 v[88:89], v[88:89], v[16:17] op_sel_hi:[1,0]
	v_pk_mul_f32 v[86:87], v[86:87], v[16:17] op_sel_hi:[1,0]
	v_mul_f32_e32 v101, v103, v101
	v_cvt_pk_bf16_f32 v101, v102, v101
	v_pk_mul_f32 v[84:85], v[84:85], v[16:17] op_sel_hi:[1,0]
	v_pk_mul_f32 v[82:83], v[82:83], v[16:17] op_sel_hi:[1,0]
	s_waitcnt lgkmcnt(0)
	s_barrier
	s_nop 1
	v_mfma_f32_16x16x32_bf16 v[94:97], v[98:101], v[180:183], v[94:97]
	v_mfma_f32_16x16x32_bf16 v[90:93], v[98:101], v[184:187], v[90:93]
	v_mfma_f32_16x16x32_bf16 v[86:89], v[98:101], v[188:191], v[86:89]
	v_mfma_f32_16x16x32_bf16 v[82:85], v[98:101], v[192:195], v[82:85]
	s_waitcnt vmcnt(8)
	ds_write_b128 v155, v[46:49]
	s_waitcnt vmcnt(7)
	ds_write_b128 v156, v[50:53]
	s_waitcnt vmcnt(6)
	ds_write_b128 v157, v[54:57]
	s_waitcnt vmcnt(5)
	ds_write_b128 v158, v[58:61]
	s_waitcnt vmcnt(4)
	ds_write_b128 v159, v[66:69]
	s_waitcnt vmcnt(3)
	ds_write_b128 v160, v[70:73]
	s_waitcnt vmcnt(2)
	ds_write_b128 v161, v[74:77]
	s_waitcnt vmcnt(1)
	ds_write_b128 v177, v[78:81]
	s_and_saveexec_b64 s[74:75], s[10:11]
	s_cbranch_execz .LBB0_847

.LBB0_870:
	s_or_b64 exec, exec, s[58:59]
	s_waitcnt lgkmcnt(0)
	s_barrier
	ds_read_b32 v216, v145
	ds_read_b32 v217, v146 offset:64000
	ds_read_b32 v218, v147
	ds_read_b32 v219, v148 offset:65024
	ds_read_b32 v220, v149
	s_add_i32 s58, s77, 1
	s_add_i32 s59, s77, -7
	s_and_b64 s[44:45], s[44:45], exec
	s_cselect_b32 s59, s58, s59
	s_sub_i32 s74, s78, s59
	s_and_b64 s[44:45], s[4:5], exec
	s_cselect_b32 s44, s59, s74
	s_cmpk_gt_u32 s58, 0x206
	v_lshl_add_u32 v222, s44, 5, v169
	v_mov_b32_e32 v221, s89
	ds_read_b32 v172, v221
	ds_read_b128 v[98:101], v170 offset:54272
	ds_read_b128 v[102:105], v151
	ds_read_b128 v[168:171], v151 offset:16
	s_waitcnt lgkmcnt(4)
	v_add_f32_e32 v216, v216, v217
	v_add_f32_e32 v218, v218, v219
	v_max_f32_e32 v220, v220, v220
	v_max_f32_e64 v218, |v218|, v220
	v_rcp_f32_e32 v218, v218
	v_ashrrev_i32_e32 v223, 31, v222
	v_lshlrev_b64 v[222:223], 11, v[222:223]
	v_mul_f32_e32 v216, v216, v218
	v_lshl_add_u64 v[222:223], v[106:107], 0, v[222:223]
	v_cvt_pk_bf16_f32 v220, v216, v17
	global_store_short v[222:223], v220, off
	ds_read_b64_tr_b16 v[180:181], v178 offset:16896
	ds_read_b64_tr_b16 v[182:183], v178 offset:19008
	ds_read_b64_tr_b16 v[184:185], v178 offset:16928
	ds_read_b64_tr_b16 v[186:187], v178 offset:19040
	ds_read_b64_tr_b16 v[188:189], v178 offset:16960
	ds_read_b64_tr_b16 v[190:191], v178 offset:19072
	ds_read_b64_tr_b16 v[192:193], v178 offset:16992
	ds_read_b64_tr_b16 v[194:195], v178 offset:19104
	s_waitcnt lgkmcnt(8)
	v_lshlrev_b32_e32 v173, 16, v98
	v_add_f32_e32 v103, v172, v103
	v_mul_f32_e32 v103, 0x3fb8aa3b, v103
	v_exp_f32_e32 v103, v103
	v_add_f32_e32 v102, v172, v102
	v_mul_f32_e32 v102, 0x3fb8aa3b, v102
	v_and_b32_e32 v98, 0xffff0000, v98
	v_exp_f32_e32 v102, v102
	v_mul_f32_e32 v98, v103, v98
	v_add_f32_e32 v103, v172, v104
	v_mul_f32_e32 v103, 0x3fb8aa3b, v103
	v_exp_f32_e32 v103, v103
	v_mul_f32_e32 v102, v102, v173
	v_cvt_pk_bf16_f32 v98, v102, v98
	v_lshlrev_b32_e32 v102, 16, v99
	v_mul_f32_e32 v102, v103, v102
	v_add_f32_e32 v103, v172, v105
	v_mul_f32_e32 v103, 0x3fb8aa3b, v103
	v_exp_f32_e32 v103, v103
	v_and_b32_e32 v99, 0xffff0000, v99
	v_mul_f32_e32 v16, 0x3fb8aa3b, v172
	v_exp_f32_e32 v16, v16
	v_mul_f32_e32 v99, v103, v99
	v_add_f32_e32 v103, v172, v168
	v_mul_f32_e32 v103, 0x3fb8aa3b, v103
	v_exp_f32_e32 v103, v103
	v_cvt_pk_bf16_f32 v99, v102, v99
	v_lshlrev_b32_e32 v102, 16, v100
	v_and_b32_e32 v100, 0xffff0000, v100
	v_mul_f32_e32 v102, v103, v102
	v_add_f32_e32 v103, v172, v169
	v_mul_f32_e32 v103, 0x3fb8aa3b, v103
	v_exp_f32_e32 v103, v103
	v_pk_mul_f32 v[96:97], v[96:97], v[16:17] op_sel_hi:[1,0]
	v_pk_mul_f32 v[94:95], v[94:95], v[16:17] op_sel_hi:[1,0]
	v_pk_mul_f32 v[92:93], v[92:93], v[16:17] op_sel_hi:[1,0]
	v_mul_f32_e32 v100, v103, v100
	v_add_f32_e32 v103, v172, v170
	v_mul_f32_e32 v103, 0x3fb8aa3b, v103
	v_exp_f32_e32 v103, v103
	v_cvt_pk_bf16_f32 v100, v102, v100
	v_lshlrev_b32_e32 v102, 16, v101
	v_and_b32_e32 v101, 0xffff0000, v101
	v_mul_f32_e32 v102, v103, v102
	v_add_f32_e32 v103, v172, v171
	v_mul_f32_e32 v103, 0x3fb8aa3b, v103
	v_exp_f32_e32 v103, v103
	v_pk_mul_f32 v[90:91], v[90:91], v[16:17] op_sel_hi:[1,0]
	v_pk_mul_f32 v[88:89], v[88:89], v[16:17] op_sel_hi:[1,0]
	v_pk_mul_f32 v[86:87], v[86:87], v[16:17] op_sel_hi:[1,0]
	v_mul_f32_e32 v101, v103, v101
	v_cvt_pk_bf16_f32 v101, v102, v101
	v_pk_mul_f32 v[84:85], v[84:85], v[16:17] op_sel_hi:[1,0]
	v_pk_mul_f32 v[82:83], v[82:83], v[16:17] op_sel_hi:[1,0]
	s_waitcnt lgkmcnt(0)
	s_barrier
	s_nop 1
	v_mfma_f32_16x16x32_bf16 v[94:97], v[98:101], v[180:183], v[94:97]
	v_mfma_f32_16x16x32_bf16 v[90:93], v[98:101], v[184:187], v[90:93]
	v_mfma_f32_16x16x32_bf16 v[86:89], v[98:101], v[188:191], v[86:89]
	v_mfma_f32_16x16x32_bf16 v[82:85], v[98:101], v[192:195], v[82:85]
	s_cbranch_scc1 .LBB0_805
	s_waitcnt vmcnt(9)
	ds_write_b128 v155, v[0:3]
	s_waitcnt vmcnt(8)
	ds_write_b128 v156, v[4:7]
	s_waitcnt vmcnt(7)
	ds_write_b128 v157, v[8:11]
	s_waitcnt vmcnt(6)
	ds_write_b128 v158, v[12:15]
	s_waitcnt vmcnt(5)
	ds_write_b128 v159, v[22:25]
	s_waitcnt vmcnt(4)
	ds_write_b128 v160, v[30:33]
	s_waitcnt vmcnt(3)
	ds_write_b128 v161, v[38:41]
	s_waitcnt vmcnt(2)
	ds_write_b128 v177, v[42:45]
	s_and_saveexec_b64 s[44:45], s[10:11]
	s_cbranch_execz .LBB0_804
	s_branch .LBB0_928
